# v11 + nt hint on P11's 16 streaming loads of UP (read-once data)
# speedup vs baseline: 1.0006x; 1.0006x over previous
.LBB0_1776:
	v_mov_b32_e32 v39, v133
	v_lshl_add_u64 v[136:137], s[46:47], 0, v[38:39]
	v_lshl_add_u64 v[40:41], v[136:137], 0, s[62:63]
	v_add_co_u32_e32 v34, vcc, 0x5000, v40
	v_lshl_add_u64 v[138:139], s[48:49], 0, v[38:39]
	s_nop 0
	v_addc_co_u32_e32 v35, vcc, 0, v41, vcc
	global_load_dwordx4 v[34:37], v[34:35], off offset:1536 nt
	s_nop 0
	global_load_dwordx4 v[70:73], v[40:41], off nt
	v_lshl_add_u64 v[40:41], v[136:137], 0, s[64:65]
	v_add_co_u32_e32 v42, vcc, 0x5000, v40
	v_mov_b64_e32 v[142:143], v[134:135]
	s_nop 0
	v_addc_co_u32_e32 v43, vcc, 0, v41, vcc
	global_load_dwordx4 v[82:85], v[42:43], off offset:1536 nt
	global_load_dwordx4 v[86:89], v[40:41], off nt
	v_lshl_add_u64 v[40:41], v[136:137], 0, s[66:67]
	v_add_co_u32_e32 v42, vcc, 0x5000, v40
	s_mov_b32 s76, s27
	s_nop 0
	v_addc_co_u32_e32 v43, vcc, 0, v41, vcc
	global_load_dwordx4 v[90:93], v[42:43], off offset:1536 nt
	global_load_dwordx4 v[94:97], v[40:41], off nt
	v_lshl_add_u64 v[40:41], v[136:137], 0, s[56:57]
	v_add_co_u32_e32 v42, vcc, 0x5000, v40
	s_nop 1
	v_addc_co_u32_e32 v43, vcc, 0, v41, vcc
	global_load_dwordx4 v[98:101], v[42:43], off offset:1536 nt
	global_load_dwordx4 v[110:113], v[40:41], off nt
	s_load_dwordx2 s[4:5], s[0:1], 0x28
	s_waitcnt lgkmcnt(0)
	v_lshl_add_u64 v[140:141], v[132:133], 2, s[4:5]
	s_branch .LBB0_1779

.LBB0_1779:
	s_add_i32 s75, s76, 4
	s_min_i32 s4, s75, s39
	v_mad_i64_i32 v[38:39], s[4:5], s4, v144, v[136:137]
	s_add_i32 s4, s76, 5
	s_min_i32 s4, s4, s39
	v_mad_i64_i32 v[46:47], s[4:5], s4, v144, v[136:137]
	v_add_co_u32_e32 v42, vcc, s41, v38
	s_add_i32 s4, s76, 6
	s_nop 0
	v_addc_co_u32_e32 v43, vcc, 0, v39, vcc
	s_min_i32 s4, s4, s39
	v_add_co_u32_e32 v50, vcc, s41, v46
	v_mad_i64_i32 v[54:55], s[4:5], s4, v144, v[136:137]
	s_nop 0
	v_addc_co_u32_e32 v51, vcc, 0, v47, vcc
	s_add_i32 s4, s76, 7
	v_add_co_u32_e32 v58, vcc, s41, v54
	s_min_i32 s4, s4, s39
	s_nop 0
	v_addc_co_u32_e32 v59, vcc, 0, v55, vcc
	v_mad_i64_i32 v[62:63], s[4:5], s4, v144, v[136:137]
	v_add_co_u32_e32 v66, vcc, s41, v62
	global_load_dwordx4 v[38:41], v[38:39], off nt
	s_nop 0
	global_load_dwordx4 v[42:45], v[42:43], off offset:1536 nt
	v_addc_co_u32_e32 v67, vcc, 0, v63, vcc
	global_load_dwordx4 v[46:49], v[46:47], off nt
	s_nop 0
	global_load_dwordx4 v[50:53], v[50:51], off offset:1536 nt
	s_nop 0
	global_load_dwordx4 v[54:57], v[54:55], off nt
	s_nop 0
	global_load_dwordx4 v[58:61], v[58:59], off offset:1536 nt
	s_nop 0
	global_load_dwordx4 v[62:65], v[62:63], off nt
	s_nop 0
	global_load_dwordx4 v[66:69], v[66:67], off offset:1536 nt
	s_add_i32 s4, s76, 0xffffe000
	s_lshr_b32 s16, s4, 3
	s_ashr_i32 s36, s76, 11
	s_cmpk_lt_i32 s76, 0x2000
	s_cselect_b64 s[72:73], -1, 0
	s_and_b64 s[4:5], s[72:73], exec
	s_cselect_b32 s4, 0x7ff, 7
	s_cselect_b32 s78, s36, s16
	s_and_b32 s77, s4, s76
	s_cmp_lg_u32 s77, 0
	s_cselect_b64 s[4:5], -1, 0
	s_or_b64 s[80:81], s[4:5], s[72:73]
	s_andn2_b64 vcc, exec, s[80:81]
	v_mad_i64_i32 v[118:119], s[80:81], s78, v145, v[140:141]
	s_cbranch_vccz .LBB0_1781
	v_add_co_u32_e32 v116, vcc, 0xa000, v118
	v_lshl_add_u64 v[114:115], v[118:119], 0, s[18:19]
	s_nop 0
	v_addc_co_u32_e32 v117, vcc, 0, v119, vcc
	global_load_dwordx4 v[122:125], v[116:117], off offset:3072
	s_nop 0
	global_load_dwordx4 v[114:117], v[114:115], off offset:16
	s_waitcnt vmcnt(0)
	s_branch .LBB0_1782
